# attention phase: static s_setprio 1 for waves 0-3
# baseline (speedup 1.0000x reference)
.LBB0_757:
	s_cmp_lt_i32 s60, 6
	s_cselect_b64 s[4:5], -1, 0
	s_and_b64 s[8:9], s[4:5], s[6:7]
	s_andn2_b64 vcc, exec, s[8:9]
	s_cbranch_vccnz .LBB0_857
	v_readfirstlane_b32 s98, v240
	s_nop 3
	s_lshr_b32 s98, s98, 8
	s_cmp_eq_u32 s98, 0
	s_cbranch_scc0 .Lattn_prio_skip
	s_setprio 1
